# weight f32->f16 transpose-conversion inner loop: all 16 row loads (+ scale loads) issued up front, one vmcnt wait, then multiply + LDS writes
# speedup vs baseline: 1.0184x; 1.0093x over previous
; #define LAS __attribute__((address_space(3)))
; __device__ __forceinline__ void tr_item(const float* src, int ld_src, int k0, int c0, f16* dst, int ld_dst, int r0, int kc0, LAS float* scr, int lane, const float* gk) {
; #pragma unroll 16
;     for (int i = 0; i < 32; ++i) { const int kk = 2 * i + (lane >> 5); scr[kk * 33 + (lane & 31)] = __builtin_nontemporal_load(src + (size_t)(k0 + kk) * ld_src + c0 + (lane & 31)) * (gk ? gk[k0 + kk] : 1.0f); }
.LBB0_38:
	v_add_u32_e32 v16, s44, v11
	v_ashrrev_i32_e32 v17, 31, v16
	v_mov_b32_e32 v44, v16
	v_ashrrev_i32_e32 v45, 31, v44
	v_mul_lo_u32 v46, s66, v45
	v_mul_lo_u32 v47, s67, v44
	v_mad_u64_u32 v[80:81], s[58:59], s66, v44, 0
	v_add3_u32 v81, v81, v46, v47
	v_lshl_add_u64 v[80:81], v[80:81], 2, v[12:13]
	global_load_dword v48, v[80:81], off nt
	v_add_u32_e32 v44, 2, v16
	v_ashrrev_i32_e32 v45, 31, v44
	v_mul_lo_u32 v46, s66, v45
	v_mul_lo_u32 v47, s67, v44
	v_mad_u64_u32 v[80:81], s[58:59], s66, v44, 0
	v_add3_u32 v81, v81, v46, v47
	v_lshl_add_u64 v[80:81], v[80:81], 2, v[12:13]
	global_load_dword v49, v[80:81], off nt
	v_add_u32_e32 v44, 4, v16
	v_ashrrev_i32_e32 v45, 31, v44
	v_mul_lo_u32 v46, s66, v45
	v_mul_lo_u32 v47, s67, v44
	v_mad_u64_u32 v[80:81], s[58:59], s66, v44, 0
	v_add3_u32 v81, v81, v46, v47
	v_lshl_add_u64 v[80:81], v[80:81], 2, v[12:13]
	global_load_dword v50, v[80:81], off nt
	v_add_u32_e32 v44, 6, v16
	v_ashrrev_i32_e32 v45, 31, v44
	v_mul_lo_u32 v46, s66, v45
	v_mul_lo_u32 v47, s67, v44
	v_mad_u64_u32 v[80:81], s[58:59], s66, v44, 0
	v_add3_u32 v81, v81, v46, v47
	v_lshl_add_u64 v[80:81], v[80:81], 2, v[12:13]
	global_load_dword v51, v[80:81], off nt
	v_add_u32_e32 v44, 8, v16
	v_ashrrev_i32_e32 v45, 31, v44
	v_mul_lo_u32 v46, s66, v45
	v_mul_lo_u32 v47, s67, v44
	v_mad_u64_u32 v[80:81], s[58:59], s66, v44, 0
	v_add3_u32 v81, v81, v46, v47
	v_lshl_add_u64 v[80:81], v[80:81], 2, v[12:13]
	global_load_dword v52, v[80:81], off nt
	v_add_u32_e32 v44, 10, v16
	v_ashrrev_i32_e32 v45, 31, v44
	v_mul_lo_u32 v46, s66, v45
	v_mul_lo_u32 v47, s67, v44
	v_mad_u64_u32 v[80:81], s[58:59], s66, v44, 0
	v_add3_u32 v81, v81, v46, v47
	v_lshl_add_u64 v[80:81], v[80:81], 2, v[12:13]
	global_load_dword v53, v[80:81], off nt
	v_add_u32_e32 v44, 12, v16
	v_ashrrev_i32_e32 v45, 31, v44
	v_mul_lo_u32 v46, s66, v45
	v_mul_lo_u32 v47, s67, v44
	v_mad_u64_u32 v[80:81], s[58:59], s66, v44, 0
	v_add3_u32 v81, v81, v46, v47
	v_lshl_add_u64 v[80:81], v[80:81], 2, v[12:13]
	global_load_dword v54, v[80:81], off nt
	v_add_u32_e32 v44, 14, v16
	v_ashrrev_i32_e32 v45, 31, v44
	v_mul_lo_u32 v46, s66, v45
	v_mul_lo_u32 v47, s67, v44
	v_mad_u64_u32 v[80:81], s[58:59], s66, v44, 0
	v_add3_u32 v81, v81, v46, v47
	v_lshl_add_u64 v[80:81], v[80:81], 2, v[12:13]
	global_load_dword v55, v[80:81], off nt
	v_add_u32_e32 v44, 16, v16
	v_ashrrev_i32_e32 v45, 31, v44
	v_mul_lo_u32 v46, s66, v45
	v_mul_lo_u32 v47, s67, v44
	v_mad_u64_u32 v[80:81], s[58:59], s66, v44, 0
	v_add3_u32 v81, v81, v46, v47
	v_lshl_add_u64 v[80:81], v[80:81], 2, v[12:13]
	global_load_dword v56, v[80:81], off nt
	v_add_u32_e32 v44, 18, v16
	v_ashrrev_i32_e32 v45, 31, v44
	v_mul_lo_u32 v46, s66, v45
	v_mul_lo_u32 v47, s67, v44
	v_mad_u64_u32 v[80:81], s[58:59], s66, v44, 0
	v_add3_u32 v81, v81, v46, v47
	v_lshl_add_u64 v[80:81], v[80:81], 2, v[12:13]
	global_load_dword v57, v[80:81], off nt
	v_add_u32_e32 v44, 20, v16
	v_ashrrev_i32_e32 v45, 31, v44
	v_mul_lo_u32 v46, s66, v45
	v_mul_lo_u32 v47, s67, v44
	v_mad_u64_u32 v[80:81], s[58:59], s66, v44, 0
	v_add3_u32 v81, v81, v46, v47
	v_lshl_add_u64 v[80:81], v[80:81], 2, v[12:13]
	global_load_dword v58, v[80:81], off nt
	v_add_u32_e32 v44, 22, v16
	v_ashrrev_i32_e32 v45, 31, v44
	v_mul_lo_u32 v46, s66, v45
	v_mul_lo_u32 v47, s67, v44
	v_mad_u64_u32 v[80:81], s[58:59], s66, v44, 0
	v_add3_u32 v81, v81, v46, v47
	v_lshl_add_u64 v[80:81], v[80:81], 2, v[12:13]
	global_load_dword v59, v[80:81], off nt
	v_add_u32_e32 v44, 24, v16
	v_ashrrev_i32_e32 v45, 31, v44
	v_mul_lo_u32 v46, s66, v45
	v_mul_lo_u32 v47, s67, v44
	v_mad_u64_u32 v[80:81], s[58:59], s66, v44, 0
	v_add3_u32 v81, v81, v46, v47
	v_lshl_add_u64 v[80:81], v[80:81], 2, v[12:13]
	global_load_dword v60, v[80:81], off nt
	v_add_u32_e32 v44, 26, v16
	v_ashrrev_i32_e32 v45, 31, v44
	v_mul_lo_u32 v46, s66, v45
	v_mul_lo_u32 v47, s67, v44
	v_mad_u64_u32 v[80:81], s[58:59], s66, v44, 0
	v_add3_u32 v81, v81, v46, v47
	v_lshl_add_u64 v[80:81], v[80:81], 2, v[12:13]
	global_load_dword v61, v[80:81], off nt
	v_add_u32_e32 v44, 28, v16
	v_ashrrev_i32_e32 v45, 31, v44
	v_mul_lo_u32 v46, s66, v45
	v_mul_lo_u32 v47, s67, v44
	v_mad_u64_u32 v[80:81], s[58:59], s66, v44, 0
	v_add3_u32 v81, v81, v46, v47
	v_lshl_add_u64 v[80:81], v[80:81], 2, v[12:13]
	global_load_dword v62, v[80:81], off nt
	v_add_u32_e32 v44, 30, v16
	v_ashrrev_i32_e32 v45, 31, v44
	v_mul_lo_u32 v46, s66, v45
	v_mul_lo_u32 v47, s67, v44
	v_mad_u64_u32 v[80:81], s[58:59], s66, v44, 0
	v_add3_u32 v81, v81, v46, v47
	v_lshl_add_u64 v[80:81], v[80:81], 2, v[12:13]
	global_load_dword v63, v[80:81], off nt
	v_mov_b32_e32 v64, 1.0
	v_mov_b32_e32 v65, 1.0
	v_mov_b32_e32 v66, 1.0
	v_mov_b32_e32 v67, 1.0
	v_mov_b32_e32 v68, 1.0
	v_mov_b32_e32 v69, 1.0
	v_mov_b32_e32 v70, 1.0
	v_mov_b32_e32 v71, 1.0
	v_mov_b32_e32 v72, 1.0
	v_mov_b32_e32 v73, 1.0
	v_mov_b32_e32 v74, 1.0
	v_mov_b32_e32 v75, 1.0
	v_mov_b32_e32 v76, 1.0
	v_mov_b32_e32 v77, 1.0
	v_mov_b32_e32 v78, 1.0
	v_mov_b32_e32 v79, 1.0
	v_cmp_ne_u32_e64 s[8:9], 1, v25
	s_andn2_b64 vcc, exec, s[72:73]
	s_cbranch_vccnz .Lwc_noscale
	v_lshl_add_u64 v[80:81], v[16:17], 2, s[62:63]
	global_load_dword v64, v[80:81], off
	global_load_dword v65, v[14:15], off offset:-112
	global_load_dword v66, v[14:15], off offset:-104
	global_load_dword v67, v[14:15], off offset:-96
	global_load_dword v68, v[14:15], off offset:-88
	global_load_dword v69, v[14:15], off offset:-80
	global_load_dword v70, v[14:15], off offset:-72
	global_load_dword v71, v[14:15], off offset:-64
	global_load_dword v72, v[14:15], off offset:-56
	global_load_dword v73, v[14:15], off offset:-48
	global_load_dword v74, v[14:15], off offset:-40
	global_load_dword v75, v[14:15], off offset:-32
	global_load_dword v76, v[14:15], off offset:-24
	global_load_dword v77, v[14:15], off offset:-16
	global_load_dword v78, v[14:15], off offset:-8
	global_load_dword v79, v[14:15], off
; #define LDS_WAIT() asm volatile("s_waitcnt lgkmcnt(0)" ::: "memory")
; __device__ __forceinline__ void tr_item(const float* src, int ld_src, int k0, int c0, f16* dst, int ld_dst, int r0, int kc0, LAS float* scr, int lane, const float* gk) {
; #pragma unroll 16
;     for (int i = 0; i < 32; ++i) { const int kk = 2 * i + (lane >> 5); scr[kk * 33 + (lane & 31)] = __builtin_nontemporal_load(src + (size_t)(k0 + kk) * ld_src + c0 + (lane & 31)) * (gk ? gk[k0 + kk] : 1.0f); }
;     LDS_WAIT();
.Lwc_noscale:
	s_waitcnt vmcnt(0)
	v_mul_f32_e32 v48, v48, v64
	ds_write_b32 v26, v48
	v_mul_f32_e32 v49, v49, v65
	ds_write_b32 v26, v49 offset:264
	v_mul_f32_e32 v50, v50, v66
	ds_write_b32 v26, v50 offset:528
	v_mul_f32_e32 v51, v51, v67
	ds_write_b32 v26, v51 offset:792
	v_mul_f32_e32 v52, v52, v68
	ds_write_b32 v26, v52 offset:1056
	v_mul_f32_e32 v53, v53, v69
	ds_write_b32 v26, v53 offset:1320
	v_mul_f32_e32 v54, v54, v70
	ds_write_b32 v26, v54 offset:1584
	v_mul_f32_e32 v55, v55, v71
	ds_write_b32 v26, v55 offset:1848
	v_mul_f32_e32 v56, v56, v72
	ds_write_b32 v26, v56 offset:2112
	v_mul_f32_e32 v57, v57, v73
	ds_write_b32 v26, v57 offset:2376
	v_mul_f32_e32 v58, v58, v74
	ds_write_b32 v26, v58 offset:2640
	v_mul_f32_e32 v59, v59, v75
	ds_write_b32 v26, v59 offset:2904
	v_mul_f32_e32 v60, v60, v76
	ds_write_b32 v26, v60 offset:3168
	v_mul_f32_e32 v61, v61, v77
	ds_write_b32 v26, v61 offset:3432
	v_mul_f32_e32 v62, v62, v78
	ds_write_b32 v26, v62 offset:3696
	v_mul_f32_e32 v63, v63, v79
	ds_write_b32 v26, v63 offset:3960
	s_add_i32 s44, s44, 32
	v_add_u32_e32 v26, 0x1080, v26
	s_cmp_lg_u32 s44, 64
	v_lshl_add_u64 v[14:15], v[14:15], 0, s[76:77]
	s_cbranch_scc1 .LBB0_38
	s_branch .LBB0_20
